# idx->attention grid barrier replaced by a counter hand-off: masks stored write-through, first DSA unit of a layer waits for all idx units; FoX/diff units start without waiting
# speedup vs baseline: 1.0192x; 1.0072x over previous
.LBB0_443:
	s_cmp_lg_u32 s96, 0
	s_cbranch_scc1 .Lgp_skip
	s_mov_b32 s100, 0
	v_readlane_b32 s0, v252, 5
	s_nop 0
	s_cmp_lg_u32 s0, 0
	s_cbranch_scc1 .Lgp_skip
	s_getreg_b32 s0, hwreg(HW_REG_XCC_ID, 0, 4)
	s_and_b32 s0, s0, 7
	s_lshl_b32 s0, s0, 2
	s_lshl_b32 s0, 1, s0
	v_mov_b32_e32 v0, s0
	v_readlane_b32 s0, v252, 0
	s_nop 0
	s_and_b32 s0, s0, 63
	s_lshl_b32 s0, s0, 2
	s_add_u32 s0, s0, 0x13500100
	s_add_u32 s0, s40, s0
	s_addc_u32 s1, s41, 0
	s_mov_b64 exec, 1
	global_atomic_add v65, v0, s[0:1]
	s_mov_b64 exec, -1

.LBB0_445:
	s_nop 0
	s_nop 0
	s_mul_i32 s0, s96, 7
	s_add_i32 s4, s0, 1
	s_cmp_ge_i32 s4, s92
	v_writelane_b32 v255, s0, 8
	s_cselect_b64 s[0:1], -1, 0
	s_cmp_lt_i32 s4, s93
	s_cselect_b64 s[4:5], -1, 0
	s_and_b64 s[4:5], s[0:1], s[4:5]
	s_mov_b64 s[0:1], -1
	s_and_b64 vcc, exec, s[4:5]
	s_cbranch_vccnz .LBB0_447
	s_mul_i32 s0, s96, 7
	s_add_i32 s26, s0, 2
	s_mov_b64 s[0:1], 0

.Lsel_store:
	s_lshl_b32 s0, s46, 2
	s_sub_i32 s0, 32, s0
	s_lshr_b32 s1, -1, s0
	v_and_b32_e32 v146, s1, v146
	s_add_i32 s0, s27, s28
	s_lshl_b32 s0, s0, 8
	s_add_u32 s0, s0, 0x13000000
	s_add_u32 s42, s40, s0
	s_addc_u32 s43, s41, 0
	global_store_dword v152, v146, s[42:43] sc1
	s_add_i32 s4, s4, 1
	s_cmp_lt_u32 s4, 2
	s_cbranch_scc1 .Lsel_row
	s_branch .LBB0_808

.LBB0_836:
	v_readlane_b32 s0, v255, 8
	s_add_i32 s26, s0, 4
	s_cmp_lt_i32 s26, s93
	s_cbranch_scc0 .LBB0_892
	s_waitcnt vmcnt(0)
	v_readlane_b32 s0, v252, 3
	v_readlane_b32 s1, v252, 4
	s_and_b64 vcc, exec, s[0:1]
	s_waitcnt lgkmcnt(0)
	s_barrier
	s_cbranch_vccnz .LBB0_891
	s_add_u32 s4, s40, 0x13503408
	s_addc_u32 s5, s41, 0
	v_mov_b32_e32 v1, 1
	s_mov_b64 exec, 1
	global_atomic_add v65, v1, s[4:5]
	s_mov_b64 s[0:1], -1

.LBB0_892:
	s_nop 0
	s_cmp_lg_u32 s96, 0
	s_cbranch_scc1 .Lgc_skip
	v_readlane_b32 s0, v252, 5
	s_nop 0
	s_cmp_lg_u32 s0, 0
	s_cbranch_scc1 .Lgc_skip
	v_readlane_b32 s0, v252, 0
	s_nop 0
	s_and_b32 s0, s0, 63
	s_lshl_b32 s0, s0, 2
	s_add_u32 s0, s0, 0x13500100
	s_add_u32 s0, s40, s0
	s_addc_u32 s1, s41, 0
	global_load_dword v0, v65, s[0:1] sc1
	s_getreg_b32 s4, hwreg(HW_REG_XCC_ID, 0, 4)
	s_and_b32 s4, s4, 15
	s_cmp_gt_u32 s4, 7
	s_cbranch_scc1 .Lgc_bad
	s_lshl_b32 s4, s4, 2
	s_lshl_b32 s4, 4, s4
	v_mov_b32_e32 v1, s4
	s_waitcnt vmcnt(0)
	v_cmp_eq_u32_e32 vcc, v0, v1
	s_cbranch_vccnz .Lgc_skip

.LBB0_1037:
	s_mul_i32 s0, s31, 5
	s_lshr_b32 s0, s30, s0
	s_bfe_u32 s26, s0, 0x30002
	s_lshl_b32 s0, s0, 5
	s_and_b32 s0, s0, 0x60
	v_readlane_b32 s1, v254, 22
	s_or_b32 s4, s0, s1
	s_cmp_gt_u32 s4, 47
	s_mov_b64 s[0:1], -1
	s_cbranch_scc0 .LBB0_1053
	s_add_i32 s5, s96, 1
	s_cmp_eq_u32 s100, s5
	s_cbranch_scc1 .Lidw_skip
	s_mov_b32 s100, s5
	s_nop 0
	v_readlane_b32 s0, v252, 5
	s_nop 0
	s_cmp_lg_u32 s0, 0
	s_cbranch_scc1 .Lidw_others
	s_add_u32 s0, s40, 0x13503408
	s_addc_u32 s1, s41, 0
	s_lshl_b32 s5, s5, 8
	v_mov_b32_e32 v1, s5
	buffer_inv sc1
	s_mov_b32 s5, 0
.Lidw_poll:
	global_load_dword v0, v65, s[0:1] sc1
	s_waitcnt vmcnt(0)
	v_cmp_ge_u32_e32 vcc, v0, v1
	s_cbranch_vccnz .Lidw_others
	s_sleep 1
	s_add_i32 s5, s5, 1
	s_cmp_lt_u32 s5, 0x80000
	s_cbranch_scc1 .Lidw_poll

.Lidw_skip:
	s_mov_b32 s5, -1
	s_sub_i32 s0, s4, 48
	v_mbcnt_lo_u32_b32 v0, s5, 0
	v_mbcnt_hi_u32_b32 v0, s5, v0
	v_readlane_b32 s5, v252, 5
	s_mul_hi_u32 s1, s0, 0xaaaaaaab
	s_mov_b64 s[6:7], s[40:41]
	v_add_u32_e32 v8, s5, v0
	s_lshr_b32 s1, s1, 2
	s_lshl_b32 s27, s0, 18
	v_readlane_b32 s34, v254, 43
	s_add_u32 s6, s6, s27
	v_readlane_b32 s35, v254, 44
	s_addc_u32 s7, s7, 0
	s_mov_b32 s39, s35
	s_lshl_b32 s38, s1, 17
	s_mov_b64 s[28:29], s[40:41]
	s_lshl_b64 s[34:35], s[38:39], 1
	s_mov_b64 s[36:37], s[40:41]
	s_mul_i32 s38, s1, 0x160000
	s_mov_b32 s43, s39
	s_lshl_b64 s[38:39], s[38:39], 1
	v_readfirstlane_b32 s5, v8
	s_add_u32 s36, s36, s38
	s_addc_u32 s37, s37, s39
	s_ashr_i32 s27, s5, 1
	s_lshl_b32 s33, s26, 8
	s_and_b32 s5, s27, 0xffffffe0
	s_add_i32 s5, s5, s33
	s_lshl_b32 s38, s26, 2
	v_ashrrev_i32_e32 v0, 3, v8
	v_ashrrev_i32_e32 v1, 31, v0
	s_add_u32 s28, s28, s34
	v_lshlrev_b64 v[2:3], 7, v[0:1]
	v_lshlrev_b32_e32 v4, 4, v8
	s_addc_u32 s29, s29, s35
	v_and_b32_e32 v64, 0x70, v4
	v_lshl_add_u64 v[132:133], s[28:29], 0, v[2:3]
	v_lshl_add_u64 v[2:3], v[132:133], 0, v[64:65]
	v_lshlrev_b64 v[4:5], 12, v[0:1]
	s_mov_b32 s28, 0x10c00000
	v_lshl_add_u64 v[134:135], s[36:37], 0, v[4:5]
	v_add_co_u32_e32 v6, vcc, s28, v2
	v_lshl_add_u64 v[4:5], v[134:135], 0, v[64:65]
	s_nop 0
	v_addc_co_u32_e32 v7, vcc, 0, v3, vcc
	s_mov_b32 s28, 0x11a80000
	s_waitcnt vmcnt(0)
	global_load_dwordx4 v[66:69], v[6:7], off
	v_add_co_u32_e32 v6, vcc, s28, v4
	v_and_b32_e32 v9, 31, v8
	s_nop 0
	v_addc_co_u32_e32 v7, vcc, 0, v5, vcc
	global_load_dwordx4 v[70:73], v[6:7], off
	v_or_b32_e32 v6, s5, v9
	s_mov_b32 s5, 0x10c02000
	v_add_co_u32_e32 v2, vcc, s5, v2
	s_mov_b64 s[28:29], 0x11a80000
	s_nop 0
	v_addc_co_u32_e32 v3, vcc, 0, v3, vcc
	v_ashrrev_i32_e32 v7, 31, v6
	v_bfe_u32 v8, v8, 5, 1
	v_lshl_add_u64 v[4:5], v[4:5], 0, s[28:29]
	global_load_dwordx4 v[74:77], v[2:3], off
	global_load_dwordx4 v[78:81], v[4:5], off offset:128
	v_lshlrev_b64 v[2:3], 7, v[6:7]
	v_lshl_add_u64 v[2:3], s[6:7], 0, v[2:3]
	v_lshlrev_b32_e32 v136, 4, v8
	v_mov_b32_e32 v137, v65
	v_lshl_add_u64 v[2:3], v[2:3], 0, v[136:137]
	s_mov_b64 s[6:7], 0x10000000
	s_brev_b32 s5, 8
	v_lshl_add_u64 v[4:5], v[2:3], 0, s[6:7]
	v_add_co_u32_e32 v2, vcc, s5, v2
	v_lshl_add_u32 v138, s1, 11, v6
	s_nop 0
	v_addc_co_u32_e32 v3, vcc, 0, v3, vcc
	v_ashrrev_i32_e32 v139, 31, v138
	global_load_dwordx4 v[82:85], v[4:5], off offset:32
	global_load_dwordx4 v[86:89], v[4:5], off offset:64
	global_load_dwordx4 v[90:93], v[2:3], off
	global_load_dwordx4 v[94:97], v[4:5], off offset:96
	s_mov_b64 s[6:7], s[40:41]
	v_lshlrev_b64 v[2:3], 8, v[138:139]
	s_mov_b32 s5, 0x13000000
	v_lshl_add_u64 v[2:3], s[6:7], 0, v[2:3]
	v_lshl_add_u64 v[2:3], v[2:3], 0, v[136:137]
	s_mov_b64 s[6:7], 0x13000000
	v_lshl_add_u64 v[4:5], v[2:3], 0, s[6:7]
	v_add_co_u32_e32 v2, vcc, s5, v2
	s_movk_i32 s34, 0x90
	s_nop 0
	v_addc_co_u32_e32 v3, vcc, 0, v3, vcc
	global_load_dwordx4 v[98:101], v[4:5], off offset:32
	global_load_dwordx4 v[102:105], v[4:5], off offset:64
	global_load_dwordx4 v[106:109], v[4:5], off offset:160
	global_load_dwordx4 v[110:113], v[4:5], off offset:192
	global_load_dwordx4 v[114:117], v[4:5], off offset:128
	global_load_dwordx4 v[118:121], v[4:5], off offset:96
	global_load_dwordx4 v[122:125], v[2:3], off
	global_load_dwordx4 v[126:129], v[4:5], off offset:224
	v_mad_u64_u32 v[0:1], s[28:29], v0, s34, v[64:65]
	v_mov_b32_e32 v131, 0
	s_mov_b32 s5, 3
	s_add_i32 s6, s38, 4
	v_lshlrev_b32_e32 v130, 2, v8
	v_add_u32_e32 v137, 0, v0
	s_or_b32 s7, s27, 31
	s_or_b32 s27, s38, 3
	v_mul_u32_u24_e32 v140, 0x90, v9
	v_mad_u32_u24 v141, v9, s34, 0
	v_lshl_add_u32 v142, v8, 5, 0
	s_sub_i32 s28, 0, s33
	s_sub_i32 s29, 0, s38
	v_mov_b32_e32 v0, 0
	v_mov_b32_e32 v1, v131
	v_mov_b32_e32 v2, v131
	v_mov_b32_e32 v3, v131
	v_mov_b32_e32 v4, v131
	v_mov_b32_e32 v5, v131
	v_mov_b32_e32 v6, v131
	v_mov_b32_e32 v7, v131
	v_mov_b32_e32 v8, v131
	v_mov_b32_e32 v9, v131
	v_mov_b32_e32 v10, v131
	v_mov_b32_e32 v11, v131
	v_mov_b32_e32 v12, v131
	v_mov_b32_e32 v13, v131
	v_mov_b32_e32 v14, v131
	v_mov_b32_e32 v15, v131
	v_mov_b32_e32 v16, v131
	v_mov_b32_e32 v17, v131
	v_mov_b32_e32 v18, v131
	v_mov_b32_e32 v19, v131
	v_mov_b32_e32 v20, v131
	v_mov_b32_e32 v21, v131
	v_mov_b32_e32 v22, v131
	v_mov_b32_e32 v23, v131
	v_mov_b32_e32 v24, v131
	v_mov_b32_e32 v25, v131
	v_mov_b32_e32 v26, v131
	v_mov_b32_e32 v27, v131
	v_mov_b32_e32 v28, v131
	v_mov_b32_e32 v29, v131
	v_mov_b32_e32 v30, v131
	v_mov_b32_e32 v31, v131
	s_waitcnt vmcnt(0) lgkmcnt(0)
	ds_write_b128 v137, v[66:69]
	ds_write_b128 v137, v[70:73] offset:18432
	s_waitcnt lgkmcnt(0)
	s_barrier
	s_branch .LBB0_1040

	.amdhsa_kernel _Z9trunk_fwd4Args
		.amdhsa_group_segment_fixed_size 0
		.amdhsa_private_segment_fixed_size 0
		.amdhsa_kernarg_size 480
		.amdhsa_user_sgpr_count 2
		.amdhsa_user_sgpr_dispatch_ptr 0
		.amdhsa_user_sgpr_queue_ptr 0
		.amdhsa_user_sgpr_kernarg_segment_ptr 1
		.amdhsa_user_sgpr_dispatch_id 0
		.amdhsa_user_sgpr_kernarg_preload_length 0
		.amdhsa_user_sgpr_kernarg_preload_offset 0
		.amdhsa_user_sgpr_private_segment_size 0
		.amdhsa_uses_dynamic_stack 0
		.amdhsa_enable_private_segment 0
		.amdhsa_system_sgpr_workgroup_id_x 1
		.amdhsa_system_sgpr_workgroup_id_y 0
		.amdhsa_system_sgpr_workgroup_id_z 0
		.amdhsa_system_sgpr_workgroup_info 0
		.amdhsa_system_vgpr_workitem_id 2
		.amdhsa_next_free_vgpr 256
		.amdhsa_next_free_sgpr 102
		.amdhsa_accum_offset 256
		.amdhsa_reserve_vcc 1
		.amdhsa_float_round_mode_32 0
		.amdhsa_float_round_mode_16_64 0
		.amdhsa_float_denorm_mode_32 3
		.amdhsa_float_denorm_mode_16_64 3
		.amdhsa_dx10_clamp 1
		.amdhsa_ieee_mode 1
		.amdhsa_fp16_overflow 0
		.amdhsa_tg_split 0
		.amdhsa_exception_fp_ieee_invalid_op 0
		.amdhsa_exception_fp_denorm_src 0
		.amdhsa_exception_fp_ieee_div_zero 0
		.amdhsa_exception_fp_ieee_overflow 0
		.amdhsa_exception_fp_ieee_underflow 0
		.amdhsa_exception_fp_ieee_inexact 0
		.amdhsa_exception_int_div_zero 0
	.end_amdhsa_kernel

amdhsa.kernels:
  - .agpr_count:     0
    .args:
      - .offset:         0
        .size:           224
        .value_kind:     by_value
      - .offset:         224
        .size:           4
        .value_kind:     hidden_block_count_x
      - .offset:         228
        .size:           4
        .value_kind:     hidden_block_count_y
      - .offset:         232
        .size:           4
        .value_kind:     hidden_block_count_z
      - .offset:         236
        .size:           2
        .value_kind:     hidden_group_size_x
      - .offset:         238
        .size:           2
        .value_kind:     hidden_group_size_y
      - .offset:         240
        .size:           2
        .value_kind:     hidden_group_size_z
      - .offset:         242
        .size:           2
        .value_kind:     hidden_remainder_x
      - .offset:         244
        .size:           2
        .value_kind:     hidden_remainder_y
      - .offset:         246
        .size:           2
        .value_kind:     hidden_remainder_z
      - .offset:         264
        .size:           8
        .value_kind:     hidden_global_offset_x
      - .offset:         272
        .size:           8
        .value_kind:     hidden_global_offset_y
      - .offset:         280
        .size:           8
        .value_kind:     hidden_global_offset_z
      - .offset:         288
        .size:           2
        .value_kind:     hidden_grid_dims
      - .offset:         312
        .size:           8
        .value_kind:     hidden_multigrid_sync_arg
      - .offset:         344
        .size:           4
        .value_kind:     hidden_dynamic_lds_size
    .group_segment_fixed_size: 0
    .kernarg_segment_align: 8
    .kernarg_segment_size: 480
    .language:       OpenCL C
    .language_version:
      - 2
      - 0
    .max_flat_workgroup_size: 512
    .name:           _Z9trunk_fwd4Args
    .private_segment_fixed_size: 0
    .sgpr_count:     108
    .sgpr_spill_count: 260
    .symbol:         _Z9trunk_fwd4Args.kd
    .uniform_work_group_size: 1
    .uses_dynamic_stack: false
    .vgpr_count:     256
    .vgpr_spill_count: 0
    .wavefront_size: 64
